# opt18: opt16 + next attention unit's Q fragment prefetched into spare VGPRs during the current unit (diff + windowed), prologue copies instead of loading
# speedup vs baseline: 1.0048x; 1.0048x over previous
; __global__ void __launch_bounds__(512, 2) fwd_megakernel(Args a) {
;     ...
;     {
;         float lam;
;         { const float v1 = a.da_lambda[lane] * a.da_lambda[64 + lane], v2 = a.da_lambda[128 + lane] * a.da_lambda[192 + lane];
;           lam = __expf(wave_sum(v1)) - __expf(wave_sum(v2)) + 0.2f; }
;         for (int i = 0; i < 8; ++i) {
;             const int id = i * G + xvcu; if (id >= 2048) break;
;             int bh = id >> 4; const int qb = id & 15; int b = bh >> 3, h = bh & 7;
;             if (G == 256) { const int v4 = xvcu >> 4; h = (i + v4) & 7; b = 2 * i + (v4 >> 3); }
;             const float slope2 = exp2f(-(float)(h + 1)) * LOG2E;
.LBB0_843:
	s_or_b64 exec, exec, s[0:1]
	s_add_u32 s0, s48, 0x5600000
	s_addc_u32 s1, s49, 0
	v_writelane_b32 v254, s0, 59
	s_waitcnt lgkmcnt(0)
	v_lshlrev_b32_e32 v0, 2, v161
	v_writelane_b32 v254, s1, 60
	s_barrier
	v_readlane_b32 s0, v254, 9
	v_readlane_b32 s1, v254, 10
	s_nop 4
	global_load_dword v1, v0, s[0:1]
	global_load_dword v2, v0, s[0:1] offset:256
	global_load_dword v4, v0, s[0:1] offset:512
	s_nop 0
	global_load_dword v0, v0, s[0:1] offset:768
	v_mbcnt_hi_u32_b32 v6, -1, v172
	v_and_b32_e32 v7, 64, v6
	v_add_u32_e32 v7, 64, v7
	v_xor_b32_e32 v8, 1, v6
	v_cmp_lt_i32_e32 vcc, v8, v7
	s_cmpk_eq_i32 s50, 0x100
	s_cselect_b64 s[0:1], -1, 0
	v_cndmask_b32_e32 v8, v6, v8, vcc
	v_lshlrev_b32_e32 v8, 2, v8
	v_readlane_b32 s2, v254, 11
	v_readlane_b32 s3, v254, 12
	v_readlane_b32 s4, v254, 13
	v_readlane_b32 s5, v254, 14
	v_readlane_b32 s6, v254, 15
	v_readlane_b32 s7, v254, 16
	v_readlane_b32 s8, v254, 17
	v_readlane_b32 s9, v254, 18
	v_readlane_b32 s10, v254, 19
	v_readlane_b32 s11, v254, 20
	v_readlane_b32 s12, v254, 21
	v_readlane_b32 s13, v254, 22
	v_readlane_b32 s14, v254, 23
	v_readlane_b32 s15, v254, 24
	v_writelane_b32 v254, s0, 61
	s_mov_b32 s10, -2.0
	s_mov_b32 s12, -4.0
	v_writelane_b32 v254, s1, 62
	s_mov_b32 s14, 0xc0c00000
	v_readlane_b32 s1, v254, 38
	s_lshr_b32 s0, s1, 4
	v_writelane_b32 v254, s0, 63
	s_ashr_i32 s0, s1, 7
	v_writelane_b32 v255, s0, 0
	s_add_i32 s0, 0, 0x12000
	v_writelane_b32 v255, s0, 2
	s_add_i32 s0, 0, 0x16000
	v_writelane_b32 v255, s0, 3
	s_add_i32 s0, 0, 0x1a000
	v_writelane_b32 v255, s0, 4
	s_add_i32 s0, 0, 0x1e000
	v_writelane_b32 v255, s0, 5
	v_writelane_b32 v255, s48, 6
	s_mov_b32 s36, 0xc1800000
	s_mov_b32 s44, 0xc1900000
	v_writelane_b32 v255, s49, 7
	s_mov_b32 s46, 0xc1a00000
	s_mov_b32 s52, 0xc1b00000
	s_mov_b32 s54, 0xc2580000
	s_mov_b32 s56, 0xc2500000
	s_mov_b32 s58, 0xc2480000
	s_mov_b32 s60, 0xc2400000
	s_mov_b32 s62, 0xc2180000
	s_mov_b32 s64, 0xc2100000
	s_mov_b32 s66, 0xc2080000
	s_mov_b32 s74, 0xc2000000
	v_writelane_b32 v255, s50, 8
	s_mov_b32 s96, 0
	v_writelane_b32 v255, s96, 20
	v_mov_b32_e32 v165, 0
	s_mov_b32 s18, 0xc2fc0000
	s_mov_b32 s11, 0xc0400000
	s_mov_b32 s13, 0xc0a00000
	s_mov_b32 s15, 0xc0e00000
	s_mov_b32 s37, 0xc1880000
	s_mov_b32 s45, 0xc1980000
	s_mov_b32 s47, 0xc1a80000
	s_mov_b32 s53, 0xc1b80000
	s_mov_b32 s55, 0xc25c0000
	s_mov_b32 s57, 0xc2540000
	s_mov_b32 s59, 0xc24c0000
	s_mov_b32 s61, 0xc2440000
	s_mov_b32 s63, 0xc21c0000
	s_mov_b32 s65, 0xc2140000
	s_mov_b32 s67, 0xc20c0000
	s_mov_b32 s75, 0xc2040000
	v_mov_b32_e32 v178, 0x358637bd
	v_mov_b32_e32 v180, 0x42800000
	v_mov_b32_e32 v183, 0x42000000
	v_writelane_b32 v255, s51, 9
	s_waitcnt vmcnt(2)
	v_mul_f32_e32 v3, v1, v2
	ds_bpermute_b32 v3, v8, v3
	s_waitcnt vmcnt(0)
	v_mul_f32_e32 v5, v4, v0
	ds_bpermute_b32 v5, v8, v5
	s_waitcnt lgkmcnt(1)
	v_fmac_f32_e32 v3, v1, v2
	v_xor_b32_e32 v1, 2, v6
	v_cmp_lt_i32_e32 vcc, v1, v7
	s_waitcnt lgkmcnt(0)
	v_fmac_f32_e32 v5, v4, v0
	v_cndmask_b32_e32 v1, v6, v1, vcc
	v_lshlrev_b32_e32 v1, 2, v1
	ds_bpermute_b32 v2, v1, v3
	ds_bpermute_b32 v0, v1, v5
	s_waitcnt lgkmcnt(1)
	v_add_f32_e32 v2, v3, v2
	v_xor_b32_e32 v3, 4, v6
	v_cmp_lt_i32_e32 vcc, v3, v7
	s_waitcnt lgkmcnt(0)
	v_add_f32_e32 v0, v5, v0
	v_cndmask_b32_e32 v3, v6, v3, vcc
	v_lshlrev_b32_e32 v3, 2, v3
	ds_bpermute_b32 v9, v3, v2
	ds_bpermute_b32 v1, v3, v0
	s_waitcnt lgkmcnt(1)
	v_add_f32_e32 v2, v2, v9
	v_xor_b32_e32 v9, 8, v6
	v_cmp_lt_i32_e32 vcc, v9, v7
	s_waitcnt lgkmcnt(0)
	v_add_f32_e32 v0, v0, v1
	v_cndmask_b32_e32 v9, v6, v9, vcc
	v_lshlrev_b32_e32 v9, 2, v9
	ds_bpermute_b32 v10, v9, v2
	ds_bpermute_b32 v1, v9, v0
	s_waitcnt lgkmcnt(1)
	v_add_f32_e32 v2, v2, v10
	v_xor_b32_e32 v10, 16, v6
	v_cmp_lt_i32_e32 vcc, v10, v7
	s_waitcnt lgkmcnt(0)
	v_add_f32_e32 v0, v0, v1
	v_cndmask_b32_e32 v10, v6, v10, vcc
	v_lshlrev_b32_e32 v181, 2, v10
	ds_bpermute_b32 v10, v181, v2
	ds_bpermute_b32 v1, v181, v0
	s_waitcnt lgkmcnt(1)
	v_add_f32_e32 v2, v2, v10
	v_xor_b32_e32 v10, 32, v6
	v_cmp_lt_i32_e32 vcc, v10, v7
	s_waitcnt lgkmcnt(0)
	v_add_f32_e32 v0, v0, v1
	v_cndmask_b32_e32 v6, v6, v10, vcc
	v_lshlrev_b32_e32 v182, 2, v6
	ds_bpermute_b32 v6, v182, v2
	ds_bpermute_b32 v1, v182, v0
	s_waitcnt lgkmcnt(1)
	v_add_f32_e32 v2, v2, v6
	s_waitcnt lgkmcnt(0)
	v_add_f32_e32 v0, v0, v1
	v_mul_f32_e32 v2, 0x3fb8aa3b, v2
	v_mul_f32_e32 v0, 0x3fb8aa3b, v0
	v_exp_f32_e32 v2, v2
	v_exp_f32_e32 v0, v0
	s_nop 0
	v_sub_f32_e32 v0, v2, v0
	v_add_f32_e32 v162, 0x3e4ccccd, v0
	v_mov_b32_e32 v163, v162
	s_branch .LBB0_846

; template <bool SWA>
; __device__ __forceinline__ void unit(LAS unsigned char* lds, const bf16_t* PROJ, const bf16_t* KT, const bf16_t* VT, bf16_t* OB, int opitch, int ocol, int b, int head, int qb, float slope2, float m_init, float lam, const float* subg) {
;     ...
;     const int q0 = SWA ? qb * 64 : qb * 128;
;     const int qw = SWA ? q0 + 32 * (wid & 1) : q0 + 32 * (wid & 3);
;     const int c = SWA ? 0 : (wid >> 2);
;     const int gq = SWA ? (wid >> 1) : 0;
;     const int qcol = SWA ? (C_SQ + (head * 4 + gq) * 64) : (C_DQ + head * 128 + c * 64);
;     const int kvh = head;
;     if (SWA) { const int hq = head * 4 + gq; slope2 = exp2f(-0.5f * (float)(hq + 1)) * LOG2E; m_init = subg[hq] * LOG2E; ocol += gq * 64; }
;     const char* Kg = (const char*)(KT + (SWA ? (size_t)(b * 4 + kvh) * SEQ * 64 : (size_t)(b * 8 + head) * SEQ * 128));
;     const char* Vg = (const char*)(VT + (SWA ? (size_t)(b * 4 + kvh) * SEQ * 64 : (size_t)(b * 8 + head) * SEQ * 128));
;     bf16x8 qf[4];
;     { const bf16_t* qp = PROJ + (size_t)(b * SEQ + qw + r) * PP + qcol + 8 * h;
; #pragma unroll
;       for (int ks = 0; ks < 4; ++ks) qf[ks] = *(const bf16x8*)(qp + 16 * ks); }
; __global__ void __launch_bounds__(512, 2) fwd_megakernel(Args a) {
;     ...
;         for (int i = 0; i < 8; ++i) {
;             const int id = i * G + xvcu; if (id >= 2048) break;
;             int bh = id >> 4; const int qb = id & 15; int b = bh >> 3, h = bh & 7;
;             if (G == 256) { const int v4 = xvcu >> 4; h = (i + v4) & 7; b = 2 * i + (v4 >> 3); }
;             const float slope2 = exp2f(-(float)(h + 1)) * LOG2E;
;             att::unit<false>(lds, PROJ, KD, VT, PROJ, PP, C_DQ + h * 128, b, h, qb, slope2, -INFINITY, lam, a.da_subnorm);
.LBB0_846:
	s_mul_i32 s0, s96, s50
	s_add_i32 s0, s0, s1
	s_cmpk_gt_i32 s0, 0x7ff
	s_mov_b64 s[6:7], -1
	s_cbranch_scc1 .LBB0_845
	s_lshr_b32 s2, s0, 4
	s_and_b32 s16, s0, 15
	s_ashr_i32 s3, s0, 7
	v_readlane_b32 s0, v254, 63
	s_add_i32 s4, s96, s0
	s_lshl_b32 s0, s96, 1
	v_readlane_b32 s1, v255, 0
	s_add_i32 s5, s0, s1
	v_readlane_b32 s0, v254, 61
	v_readlane_b32 s1, v254, 62
	s_and_b64 s[0:1], s[0:1], exec
	s_cselect_b32 s1, s4, s2
	s_cselect_b32 s0, s5, s3
	s_and_b32 s1, s1, 7
	s_add_i32 s2, s1, 1
	v_cvt_f32_ubyte0_e32 v0, s2
	s_mov_b32 s2, 0x42fc0000
	v_cmp_lt_f32_e32 vcc, s2, v0
	v_mov_b32_e32 v184, v246
	s_and_b64 s[2:3], vcc, exec
	v_cndmask_b32_e32 v1, 0, v180, vcc
	v_sub_f32_e32 v0, v1, v0
	v_exp_f32_e32 v0, v0
	s_cselect_b32 s2, 0xffffffc0, 0
	v_readfirstlane_b32 s9, v184
	s_ashr_i32 s3, s9, 6
	v_ldexp_f32 v0, v0, s2
	s_and_b32 s2, s3, 3
	s_lshl_b32 s42, s16, 7
	s_mov_b32 s70, s2
	s_lshl_b32 s2, s2, 5
	v_and_b32_e32 v185, 31, v184
	s_or_b32 s5, s2, s42
	v_mul_f32_e32 v0, 0x3fb8aa3b, v0
	s_lshl_b32 s69, s0, 11
	v_or_b32_e32 v188, s5, v185
	v_readfirstlane_b32 s76, v0
	s_ashr_i32 s4, s9, 8
	v_or_b32_e32 v0, s69, v188
	s_lshl_b32 s6, s1, 7
	v_writelane_b32 v255, s2, 10
	s_lshl_b32 s2, s4, 6
	v_ashrrev_i32_e32 v1, 31, v0
	s_mov_b32 s68, s6
	s_add_i32 s6, s2, s6
	v_lshlrev_b64 v[0:1], 13, v[0:1]
	v_bfe_u32 v32, v184, 5, 1
	v_lshl_add_u64 v[0:1], s[20:21], 0, v[0:1]
	s_ashr_i32 s7, s6, 31
	v_lshl_add_u64 v[0:1], s[6:7], 1, v[0:1]
	v_lshlrev_b32_e32 v166, 4, v32
	v_mov_b32_e32 v167, v165
	v_lshl_add_u64 v[0:1], v[0:1], 0, v[166:167]
	v_lshl_add_u32 v247, v188, 13, v166
	v_readlane_b32 s84, v255, 20
	s_cmp_lg_u32 s84, 0
	s_cbranch_scc1 .Ldq_have
	global_load_dwordx4 v[140:143], v[0:1], off
	global_load_dwordx4 v[136:139], v[0:1], off offset:32
	global_load_dwordx4 v[132:135], v[0:1], off offset:64
	global_load_dwordx4 v[128:131], v[0:1], off offset:96
	s_branch .Ldq_done
.Ldq_have:
	s_mov_b32 s84, 0
	v_writelane_b32 v255, s84, 20
	v_mov_b32_e32 v140, v236
	v_mov_b32_e32 v141, v237
	v_mov_b32_e32 v142, v238
	v_mov_b32_e32 v143, v239
	v_mov_b32_e32 v136, v240
	v_mov_b32_e32 v137, v241
	v_mov_b32_e32 v138, v242
	v_mov_b32_e32 v139, v243
	v_mov_b32_e32 v132, v248
	v_mov_b32_e32 v133, v249
	v_mov_b32_e32 v134, v250
	v_mov_b32_e32 v135, v251
	v_mov_b32_e32 v128, v244
	v_mov_b32_e32 v129, v245
	v_mov_b32_e32 v130, v252
	v_mov_b32_e32 v131, v253
.Ldq_done:
	v_cmp_gt_i32_e32 vcc, 32, v184
	v_lshlrev_b32_e32 v16, 1, v184
	s_and_saveexec_b64 s[6:7], vcc
	s_cbranch_execz .LBB0_849
	v_and_b32_e32 v0, 7, v184
	v_and_or_b32 v0, v16, 16, v0
	v_cvt_f32_ubyte0_e32 v0, v0
	v_mul_f32_e32 v0, s76, v0
	v_cmp_gt_i32_e32 vcc, 16, v184
	v_lshl_add_u32 v1, v184, 2, 0
	v_add_u32_e32 v1, 0x20200, v1
	v_cndmask_b32_e64 v0, -v0, v0, vcc
	ds_write_b32 v1, v0
; #define DMA_T(s_) do { DMA_K(s_); DMA_V(s_); } while (0)
; #define WAIT_BAR() do { asm volatile("s_waitcnt vmcnt(0) lgkmcnt(0)" ::: "memory"); __builtin_amdgcn_s_barrier(); asm volatile("" ::: "memory"); } while (0)
; #define CLASSIFY(kv0_, act_, cls_) do { act_ = true; if (SWA) act_ = ((kv0_) + 63 >= qw - 128) && ((kv0_) <= qw + 159); \
;         cls_ = 0; if ((kv0_) + 63 < qw) cls_ = 1; else if ((kv0_) > qw + 31) cls_ = 2; \
;         if (SWA) { if (cls_ == 1 && qw + 31 - (kv0_) > 128) cls_ = 0; if (cls_ == 2 && (kv0_) + 63 - qw > 128) cls_ = 0; } } while (0)
; template <bool SWA>
; __device__ __forceinline__ void unit(LAS unsigned char* lds, const bf16_t* PROJ, const bf16_t* KT, const bf16_t* VT, bf16_t* OB, int opitch, int ocol, int b, int head, int qb, float slope2, float m_init, float lam, const float* subg) {
;     ...
;     unsigned gK[NCH], gV[NCH];
; #pragma unroll
;     for (int i = 0; i < NCH; ++i) {
;         const int p = NCH * wid + i;
;         if (SWA) { const int row = 8 * p + (lane >> 3), ch = (lane & 7) ^ ((row >> 1) & 7); gK[i] = (unsigned)(row * 128 + ch * 16); }
;         else { const int row = 4 * p + (lane >> 4), ch = (lane & 15) ^ (row & 15); gK[i] = (unsigned)(row * 256 + ch * 16); }
;         { const int d = 8 * p + (lane >> 3), ch = (lane & 7) ^ ((d >> 1) & 7); gV[i] = (unsigned)(d * 128 + ch * 16); }
;     }
;     const unsigned pw = (unsigned)(NCH * wid) * 1024u;
;     const unsigned lds0 = (unsigned)(uintptr_t)lds;
;     ...
;     WAIT_BAR();
;     const int npairs = (nsteps + 1) >> 1;
;     for (int S = 0; S < npairs; ++S) {
;         const int sa = 2 * S, sb = 2 * S + 1;
;         if (sa + 2 < nsteps) DMA_T(sa + 2);
;         if (sb + 2 < nsteps) DMA_T(sb + 2);
;         const int kva = TILE_OF(sa) * 64, kvb = TILE_OF(sb < nsteps ? sb : sa) * 64;
;         bool acta, actb; int clsa, clsb;
;         CLASSIFY(kva, acta, clsa); CLASSIFY(kvb, actb, clsb); actb = actb && (sb < nsteps);
.LBB0_849:
	s_or_b64 exec, exec, s[6:7]
	s_lshl_b32 s0, s0, 3
	s_or_b32 s0, s0, s1
	s_ashr_i32 s1, s0, 31
	s_lshl_b64 s[0:1], s[0:1], 19
	v_readlane_b32 s6, v254, 57
	v_readlane_b32 s7, v254, 58
	s_add_u32 s73, s6, s0
	s_addc_u32 s17, s7, s1
	v_readlane_b32 s6, v254, 59
	v_and_b32_e32 v186, 63, v184
	v_readlane_b32 s7, v254, 60
	s_add_u32 s2, s6, s0
	s_addc_u32 s23, s7, s1
	v_lshrrev_b32_e32 v0, 4, v186
	s_lshl_b32 s1, s3, 3
	v_or_b32_e32 v2, s1, v0
	v_bitop3_b32 v3, s1, v184, v0 bitop3:0x36
	s_lshl_b32 s0, s3, 1
	v_lshlrev_b32_e32 v2, 8, v2
	v_lshlrev_b32_e32 v3, 4, v3
	s_movk_i32 s6, 0xf0
	v_lshrrev_b32_e32 v1, 3, v186
	v_and_or_b32 v164, v3, s6, v2
	s_lshl_b32 s33, s3, 11
	v_lshlrev_b32_e32 v167, 4, v184
	v_and_b32_e32 v3, 48, v184
	s_movk_i32 s3, 0x70
	s_or_b32 s0, s0, 1
	v_lshlrev_b32_e32 v2, 7, v1
	v_bitop3_b32 v3, v167, v3, s3 bitop3:0x6c
	s_lshl_b32 s1, s0, 2
	v_or3_b32 v168, v2, v3, s33
	v_or_b32_e32 v2, s1, v0
	v_bitop3_b32 v0, s1, v184, v0 bitop3:0x36
	v_lshlrev_b32_e32 v2, 8, v2
	v_lshlrev_b32_e32 v0, 4, v0
	v_and_or_b32 v170, v0, s6, v2
	v_lshl_or_b32 v0, s0, 3, v1
	v_lshrrev_b32_e32 v1, 1, v0
	v_xor_b32_e32 v1, v1, v184
	v_lshlrev_b32_e32 v0, 7, v0
	v_lshlrev_b32_e32 v1, 4, v1
	v_and_or_b32 v172, v1, s3, v0
	s_lshl_b32 s3, s16, 15
	s_add_u32 s0, s73, s3
	s_addc_u32 s1, s17, 0
	s_add_i32 s33, s33, 0
	v_lshl_add_u64 v[0:1], s[0:1], 0, v[164:165]
	s_mov_b32 s6, m0
	s_mov_b32 m0, s33
	s_nop 0
	global_load_lds_dwordx4 v[0:1], off
	s_mov_b32 m0, s6
	v_mov_b32_e32 v171, v165
	s_add_i32 s6, s33, 0x400
	v_lshl_add_u64 v[0:1], s[0:1], 0, v[170:171]
	s_mov_b32 s7, m0
	s_mov_b32 m0, s6
	s_nop 0
	global_load_lds_dwordx4 v[0:1], off
	s_mov_b32 m0, s7
	s_add_u32 s6, s2, s3
	s_addc_u32 s7, s23, 0
	v_mov_b32_e32 v169, v165
	s_add_i32 s72, s33, 0x10000
	v_lshl_add_u64 v[0:1], s[6:7], 0, v[168:169]
	s_mov_b32 s3, m0
	s_mov_b32 m0, s72
	s_nop 0
	global_load_lds_dwordx4 v[0:1], off
	s_mov_b32 m0, s3
	s_add_i32 s3, s33, 0x10400
	v_mov_b32_e32 v173, v165
	s_add_u32 s0, s0, 0x4000
	v_lshl_add_u64 v[0:1], s[6:7], 0, v[172:173]
	s_addc_u32 s1, s1, 0
	s_mov_b32 s8, m0
	s_mov_b32 m0, s3
	s_nop 0
	global_load_lds_dwordx4 v[0:1], off
	s_mov_b32 m0, s8
	v_lshl_add_u64 v[0:1], s[0:1], 0, v[164:165]
	s_add_i32 s3, s33, 0x4000
	s_mov_b32 s8, m0
	s_mov_b32 m0, s3
	s_nop 0
	global_load_lds_dwordx4 v[0:1], off
	s_mov_b32 m0, s8
	v_lshl_add_u64 v[0:1], s[0:1], 0, v[170:171]
	s_add_i32 s0, s33, 0x4400
	s_mov_b32 s1, m0
	s_mov_b32 m0, s0
	s_nop 0
	global_load_lds_dwordx4 v[0:1], off
	s_mov_b32 m0, s1
	s_add_u32 s0, s6, 0x4000
	s_addc_u32 s1, s7, 0
	v_lshl_add_u64 v[0:1], s[0:1], 0, v[168:169]
	s_add_i32 s3, s33, 0x14000
	s_mov_b32 s6, m0
	s_mov_b32 m0, s3
	s_nop 0
	global_load_lds_dwordx4 v[0:1], off
	s_mov_b32 m0, s6
	v_lshl_add_u64 v[0:1], s[0:1], 0, v[172:173]
	s_add_i32 s0, s33, 0x14400
	s_or_b32 s19, s5, 31
	s_cmp_eq_u32 s16, 0
	s_mov_b32 s1, m0
	s_mov_b32 m0, s0
	s_nop 0
	global_load_lds_dwordx4 v[0:1], off
	s_mov_b32 m0, s1
	s_cselect_b32 s3, 0x8000, 0
	s_mov_b32 s0, 0xc000
	s_cselect_b32 s6, s0, 0x4000
	s_add_u32 s0, s73, s3
	s_addc_u32 s1, s17, 0
	s_waitcnt vmcnt(0)
	s_waitcnt vmcnt(0) lgkmcnt(0)
	s_barrier
	s_cmpk_eq_i32 s50, 0x100
	s_cbranch_scc0 .Ldq_nopf
	s_cmp_lt_u32 s96, 7
	s_cbranch_scc0 .Ldq_nopf
	s_add_i32 s86, s69, 0x1000
	s_lshl_b32 s86, s86, 13
	s_add_i32 s87, s68, 0x80
	s_and_b32 s87, s87, 0x380
	v_readfirstlane_b32 s85, v246
	s_lshr_b32 s85, s85, 8
	s_lshl_b32 s85, s85, 6
	s_add_i32 s87, s87, s85
	s_lshl_b32 s87, s87, 1
	s_add_i32 s86, s86, s87
	s_add_u32 s84, s20, s86
	s_addc_u32 s85, s21, 0
	global_load_dwordx4 v[236:239], v247, s[84:85]
	global_load_dwordx4 v[240:243], v247, s[84:85] offset:32
	global_load_dwordx4 v[248:251], v247, s[84:85] offset:64
	global_load_dwordx2 v[244:245], v247, s[84:85] offset:96
	global_load_dwordx2 v[252:253], v247, s[84:85] offset:104
	s_mov_b32 s86, 1
	v_writelane_b32 v255, s86, 20
.Ldq_nopf:
	v_lshl_add_u64 v[0:1], s[0:1], 0, v[164:165]
	s_add_i32 s7, s33, 0x8000
	s_mov_b32 s8, m0
	s_mov_b32 m0, s7
	s_nop 0
	global_load_lds_dwordx4 v[0:1], off
	s_mov_b32 m0, s8
	v_lshl_add_u64 v[0:1], s[0:1], 0, v[170:171]
	s_add_i32 s0, s33, 0x8400
	s_mov_b32 s1, m0
	s_mov_b32 m0, s0
	s_nop 0
	global_load_lds_dwordx4 v[0:1], off
	s_mov_b32 m0, s1
	s_add_u32 s0, s2, s3
	s_addc_u32 s1, s23, 0
	v_lshl_add_u64 v[0:1], s[0:1], 0, v[168:169]
	s_add_i32 s3, s33, 0x18000
	s_mov_b32 s7, m0
	s_mov_b32 m0, s3
	s_nop 0
	global_load_lds_dwordx4 v[0:1], off
	s_mov_b32 m0, s7
	v_lshl_add_u64 v[0:1], s[0:1], 0, v[172:173]
	s_add_i32 s0, s33, 0x18400
	s_mov_b32 s1, m0
	s_mov_b32 m0, s0
	s_nop 0
	global_load_lds_dwordx4 v[0:1], off
	s_mov_b32 m0, s1
	s_add_u32 s0, s73, s6
	s_addc_u32 s1, s17, 0
	v_lshl_add_u64 v[0:1], s[0:1], 0, v[164:165]
	s_add_i32 s3, s33, 0xc000
	s_mov_b32 s7, m0
	s_mov_b32 m0, s3
	s_nop 0
	global_load_lds_dwordx4 v[0:1], off
	s_mov_b32 m0, s7
	v_lshl_add_u64 v[0:1], s[0:1], 0, v[170:171]
	s_add_i32 s0, s33, 0xc400
	s_mov_b32 s1, m0
	s_mov_b32 m0, s0
	s_nop 0
	global_load_lds_dwordx4 v[0:1], off
	s_mov_b32 m0, s1
	s_add_u32 s0, s2, s6
	s_addc_u32 s1, s23, 0
	v_lshl_add_u64 v[0:1], s[0:1], 0, v[168:169]
	s_add_i32 s3, s33, 0x1c000
	s_mov_b32 s6, m0
	s_mov_b32 m0, s3
	s_nop 0
	global_load_lds_dwordx4 v[0:1], off
	s_mov_b32 m0, s6
	v_lshl_add_u64 v[0:1], s[0:1], 0, v[172:173]
	s_add_i32 s0, s33, 0x1c400
	s_mov_b32 s1, m0
	s_mov_b32 m0, s0
	s_nop 0
	global_load_lds_dwordx4 v[0:1], off
	s_mov_b32 m0, s1
	s_or_b32 s0, s42, 63
	s_cmp_ge_u32 s0, s5
	s_cselect_b64 s[6:7], -1, 0
	s_cmp_lt_u32 s0, s5
	s_cselect_b64 s[82:83], -1, 0
	s_cmp_le_u32 s42, s19
	s_cselect_b64 s[78:79], -1, 0
	s_and_b64 s[84:85], s[6:7], s[78:79]
	s_and_b64 vcc, exec, s[84:85]
	v_mov_b32_e32 v64, 0
	s_cbranch_vccnz .LBB0_851
	s_and_b64 s[0:1], s[78:79], exec
	s_cselect_b32 s3, 0, 64
	s_and_b64 s[0:1], s[6:7], exec
	s_cselect_b32 s0, s3, 0
	s_add_i32 s0, s0, 0
	s_add_i32 s0, s0, 0x20200
	v_mov_b32_e32 v12, s0
	ds_read_b128 v[0:3], v12
	ds_read_b128 v[4:7], v12 offset:16
	ds_read_b128 v[8:11], v12 offset:32
	ds_read_b128 v[12:15], v12 offset:48
	s_branch .LBB0_852

; __global__ void __launch_bounds__(512, 2) fwd_megakernel(Args a) {
;     ...
;         for (int i = 0; i < 8; ++i) {
;             const int id = i * G + xvcu; if (id >= 2048) break;
;             const int qb = id & 31, bk = id >> 5, b = bk >> 2, kvh = bk & 3;
;             att::unit<true>(lds, PROJ, KS, VTS, PROJ, PP, C_SQ + kvh * 256, b, kvh, qb, 0.f, 0.f, 0.f, a.swa_sink);
.LBB0_954:
	s_add_u32 s0, s48, 0x9600000
	v_writelane_b32 v255, s0, 10
	s_addc_u32 s0, s49, 0
	v_writelane_b32 v254, s0, 63
	s_mov_b32 s3, 0
	v_writelane_b32 v255, s2, 0
	s_mov_b32 s36, 0xc2000000
	s_mov_b32 s38, -2.0
	s_mov_b32 s42, 0xc2080000
	s_mov_b32 s44, -4.0
	s_mov_b32 s46, 0xc2100000
	s_mov_b32 s52, 0xc0c00000
	s_mov_b32 s54, 0xc2180000
	s_mov_b32 s56, 0xc1800000
	s_mov_b32 s58, 0xc2400000
	s_mov_b32 s60, 0xc1900000
	s_mov_b32 s62, 0xc2480000
	s_mov_b32 s64, 0xc1a00000
	s_mov_b32 s66, 0xc2500000
	s_mov_b32 s74, 0xc1b00000
	s_mov_b32 s76, 0xc2580000
	v_readlane_b32 s70, v254, 54
	v_writelane_b32 v255, s3, 1
	v_mov_b32_e32 v1, 0
	s_mov_b32 s4, 0xc2fc0000
	s_mov_b64 s[14:15], 0x2000
	s_mov_b32 s37, 0xc2040000
	s_mov_b32 s39, 0xc0400000
	s_mov_b32 s43, 0xc20c0000
	s_mov_b32 s45, 0xc0a00000
	s_mov_b32 s47, 0xc2140000
	s_mov_b32 s53, 0xc0e00000
	s_mov_b32 s55, 0xc21c0000
	s_mov_b32 s57, 0xc1880000
	s_mov_b32 s59, 0xc2440000
	s_mov_b32 s61, 0xc1980000
	s_mov_b32 s63, 0xc24c0000
	s_mov_b32 s65, 0xc1a80000
	s_mov_b32 s67, 0xc2540000
	s_mov_b32 s75, 0xc1b80000
	s_mov_b32 s77, 0xc25c0000
	s_mov_b32 s5, 0x43000000
	v_mov_b32_e32 v140, 0x42800000
	v_not_b32_e32 v141, 63
	v_mov_b32_e32 v142, 0xff800000
	s_mov_b32 s16, s1
	s_mov_b32 s17, 0
	s_mov_b32 s32, 0
	v_readlane_b32 s68, v254, 53
	v_readlane_b32 s71, v254, 55
	v_readlane_b32 s69, v254, 56
	s_branch .LBB0_958

; template <bool SWA>
; __device__ __forceinline__ void unit(LAS unsigned char* lds, const bf16_t* PROJ, const bf16_t* KT, const bf16_t* VT, bf16_t* OB, int opitch, int ocol, int b, int head, int qb, float slope2, float m_init, float lam, const float* subg) {
;     ...
;     const int q0 = SWA ? qb * 64 : qb * 128;
;     const int qw = SWA ? q0 + 32 * (wid & 1) : q0 + 32 * (wid & 3);
;     const int c = SWA ? 0 : (wid >> 2);
;     const int gq = SWA ? (wid >> 1) : 0;
;     const int qcol = SWA ? (C_SQ + (head * 4 + gq) * 64) : (C_DQ + head * 128 + c * 64);
;     const int kvh = head;
;     if (SWA) { const int hq = head * 4 + gq; slope2 = exp2f(-0.5f * (float)(hq + 1)) * LOG2E; m_init = subg[hq] * LOG2E; ocol += gq * 64; }
;     const char* Kg = (const char*)(KT + (SWA ? (size_t)(b * 4 + kvh) * SEQ * 64 : (size_t)(b * 8 + head) * SEQ * 128));
;     const char* Vg = (const char*)(VT + (SWA ? (size_t)(b * 4 + kvh) * SEQ * 64 : (size_t)(b * 8 + head) * SEQ * 128));
;     bf16x8 qf[4];
;     { const bf16_t* qp = PROJ + (size_t)(b * SEQ + qw + r) * PP + qcol + 8 * h;
; #pragma unroll
;       for (int ks = 0; ks < 4; ++ks) qf[ks] = *(const bf16x8*)(qp + 16 * ks); }
; __global__ void __launch_bounds__(512, 2) fwd_megakernel(Args a) {
;     ...
;         for (int i = 0; i < 8; ++i) {
;             const int id = i * G + xvcu; if (id >= 2048) break;
;             const int qb = id & 31, bk = id >> 5, b = bk >> 2, kvh = bk & 3;
;             att::unit<true>(lds, PROJ, KS, VTS, PROJ, PP, C_SQ + kvh * 256, b, kvh, qb, 0.f, 0.f, 0.f, a.swa_sink);
.LBB0_958:
	s_mul_i32 s2, s17, s50
	s_add_i32 s2, s2, s1
	s_cmpk_gt_i32 s2, 0x7ff
	s_mov_b64 s[6:7], -1
	s_cbranch_scc1 .LBB0_957
	v_mov_b32_e32 v143, v246
	s_and_b32 s0, s2, 31
	v_readfirstlane_b32 s19, v143
	s_ashr_i32 s22, s19, 6
	s_lshl_b32 s3, s22, 5
	s_ashr_i32 s1, s2, 7
	s_bfe_u32 s23, s2, 0x20005
	s_lshl_b32 s2, s0, 6
	s_and_b32 s7, s3, 32
	s_or_b32 s25, s7, s2
	s_ashr_i32 s24, s19, 7
	s_lshl_b32 s2, s23, 2
	s_add_i32 s8, s24, s2
	v_readlane_b32 s80, v254, 9
	s_ashr_i32 s9, s8, 31
	v_readlane_b32 s84, v254, 13
	v_readlane_b32 s85, v254, 14
	s_lshl_b32 s10, s8, 6
	s_lshl_b64 s[12:13], s[8:9], 2
	s_mov_b64 s[72:73], s[84:85]
	s_add_u32 s12, s72, s12
	s_addc_u32 s13, s73, s13
	s_lshl_b32 s3, s1, 11
	v_and_b32_e32 v144, 31, v143
	s_or_b32 s18, s25, s3
	v_or_b32_e32 v4, s18, v144
	v_ashrrev_i32_e32 v5, 31, v4
	v_lshlrev_b64 v[4:5], 13, v[4:5]
	v_bfe_u32 v2, v143, 5, 1
	v_lshl_add_u64 v[4:5], s[20:21], 0, v[4:5]
	s_ashr_i32 s11, s10, 31
	v_lshl_add_u64 v[4:5], s[10:11], 1, v[4:5]
	v_lshlrev_b32_e32 v0, 4, v2
	v_lshl_add_u64 v[4:5], v[4:5], 0, v[0:1]
	global_load_dword v3, v1, s[12:13]
	v_or_b32_e32 v247, s25, v144
	v_lshl_add_u32 v247, v247, 13, v0
	s_cmp_lg_u32 s32, 0
	s_cbranch_scc1 .Lsq_have
	global_load_dwordx4 v[98:101], v[4:5], off offset:2048
	global_load_dwordx4 v[102:105], v[4:5], off offset:2080
	global_load_dwordx4 v[106:109], v[4:5], off offset:2112
	global_load_dwordx4 v[110:113], v[4:5], off offset:2144
	s_branch .Lsq_done
.Lsq_have:
	s_mov_b32 s32, 0
	v_mov_b32_e32 v98, v230
	v_mov_b32_e32 v99, v231
	v_mov_b32_e32 v100, v232
	v_mov_b32_e32 v101, v233
	v_mov_b32_e32 v102, v234
	v_mov_b32_e32 v103, v235
	v_mov_b32_e32 v104, v236
	v_mov_b32_e32 v105, v237
	v_mov_b32_e32 v106, v238
	v_mov_b32_e32 v107, v239
	v_mov_b32_e32 v108, v240
	v_mov_b32_e32 v109, v241
	v_mov_b32_e32 v110, v242
	v_mov_b32_e32 v111, v243
	v_mov_b32_e32 v112, v244
	v_mov_b32_e32 v113, v245
.Lsq_done:
	s_movk_i32 s3, 0x80
	v_cmp_gt_i32_e32 vcc, s3, v143
	v_lshlrev_b32_e32 v4, 1, v143
	v_readlane_b32 s81, v254, 10
	v_readlane_b32 s82, v254, 11
	v_readlane_b32 s83, v254, 12
	v_readlane_b32 s86, v254, 15
	v_readlane_b32 s87, v254, 16
	v_readlane_b32 s88, v254, 17
	v_readlane_b32 s89, v254, 18
	v_readlane_b32 s90, v254, 19
	v_readlane_b32 s91, v254, 20
	v_readlane_b32 s92, v254, 21
	v_readlane_b32 s93, v254, 22
	v_readlane_b32 s94, v254, 23
	v_readlane_b32 s95, v254, 24
	s_and_saveexec_b64 s[10:11], vcc
	s_cbranch_execz .LBB0_961
	v_ashrrev_i32_e32 v0, 5, v143
	v_add3_u32 v0, v0, s2, 1
	v_cvt_f32_i32_e32 v0, v0
	v_mul_f32_e32 v5, -0.5, v0
	v_cmp_gt_f32_e32 vcc, s4, v5
	s_nop 1
	v_cndmask_b32_e32 v5, 0, v140, vcc
	v_fmac_f32_e32 v5, -0.5, v0
	v_exp_f32_e32 v0, v5
	v_cndmask_b32_e32 v5, 0, v141, vcc
	v_ldexp_f32 v0, v0, v5
	v_and_b32_e32 v5, 7, v143
	v_and_or_b32 v5, v4, 16, v5
	v_mul_f32_e32 v0, 0x3fb8aa3b, v0
	v_cvt_f32_ubyte0_e32 v5, v5
	v_mul_f32_e32 v0, v0, v5
	v_and_b32_e32 v5, 16, v143
	v_cmp_eq_u32_e32 vcc, 0, v5
	v_lshl_add_u32 v5, v143, 2, 0
	v_add_u32_e32 v5, 0x20200, v5
	v_cndmask_b32_e64 v0, -v0, v0, vcc
	ds_write_b32 v5, v0

; #define WAIT_BAR() do { asm volatile("s_waitcnt vmcnt(0) lgkmcnt(0)" ::: "memory"); __builtin_amdgcn_s_barrier(); asm volatile("" ::: "memory"); } while (0)
; template <bool SWA>
; __device__ __forceinline__ void unit(LAS unsigned char* lds, const bf16_t* PROJ, const bf16_t* KT, const bf16_t* VT, bf16_t* OB, int opitch, int ocol, int b, int head, int qb, float slope2, float m_init, float lam, const float* subg) {
;     ...
;     { const bf16_t* qp = PROJ + (size_t)(b * SEQ + qw + r) * PP + qcol + 8 * h;
; #pragma unroll
;       for (int ks = 0; ks < 4; ++ks) qf[ks] = *(const bf16x8*)(qp + 16 * ks); }
;     ...
;     f32x16 o[NDB];
; #pragma unroll
;     for (int db = 0; db < NDB; ++db)
; #pragma unroll
;         for (int i = 0; i < 16; ++i) o[db][i] = 0.f;
;     float mrun = m_init, lrun = (SWA && h == 0) ? 1.0f : 0.0f;
;     const int krow = (r & 0x13) | ((r & 4) << 1) | ((r & 8) >> 1);
;     int offK[4], offV[4];
; #pragma unroll
;     for (int ks = 0; ks < 4; ++ks) {
;         if (SWA) offK[ks] = krow * 128 + (((2 * ks + h) ^ ((krow >> 1) & 7)) << 4);
;         else offK[ks] = krow * 256 + (((c * 8 + 2 * ks + h) ^ (krow & 15)) << 4);
;         offV[ks] = r * 128 + (((2 * ks + h) ^ ((r >> 1) & 7)) << 4);
;     }
;     bf16x8 pf[4]; bool pvalid = false;
;     asm volatile("" : "+v"(qf[0]), "+v"(qf[1]), "+v"(qf[2]), "+v"(qf[3]));
;     WAIT_BAR();
;     const int npairs = (nsteps + 1) >> 1;
.LBB0_963:
	s_waitcnt vmcnt(0)
	s_waitcnt vmcnt(0) lgkmcnt(0)
	s_barrier
	s_add_i32 s0, s0, 6
	v_cmp_gt_u32_e32 vcc, 32, v5
	s_ashr_i32 s12, s0, 1
	v_lshlrev_b32_e32 v146, 3, v2
	v_cndmask_b32_e64 v147, 0, 1.0, vcc
	s_cmp_lt_i32 s12, 1
	s_cbranch_scc1 .LBB0_1013
	s_cmpk_eq_i32 s50, 0x100
	s_cbranch_scc0 .Lsq_nopf
	s_cmp_lt_u32 s17, 7
	s_cbranch_scc0 .Lsq_nopf
	s_lshr_b32 s100, s18, 11
	s_add_i32 s100, s100, 2
	s_lshl_b32 s100, s100, 24
	s_lshl_b32 s101, s23, 9
	s_add_i32 s100, s100, s101
	s_lshl_b32 s101, s24, 7
	s_add_i32 s100, s100, s101
	s_addk_i32 s100, 0x800
	s_add_u32 s98, s20, s100
	s_addc_u32 s99, s21, 0
	global_load_dwordx4 v[230:233], v247, s[98:99]
	global_load_dwordx4 v[234:237], v247, s[98:99] offset:32
	global_load_dwordx4 v[238:241], v247, s[98:99] offset:64
	global_load_dwordx4 v[242:245], v247, s[98:99] offset:96
	s_mov_b32 s32, 1
.Lsq_nopf:
	v_lshrrev_b32_e32 v6, 1, v143
	v_and_b32_e32 v5, 19, v143
	v_and_b32_e32 v4, 8, v4
	v_and_b32_e32 v7, 4, v6
	v_or3_b32 v4, v4, v5, v7
	v_lshlrev_b32_e32 v7, 7, v144
	v_bitop3_b32 v6, v2, v6, 7 bitop3:0x78
	v_lshlrev_b32_e32 v5, 7, v4
	v_lshrrev_b32_e32 v4, 1, v4
	v_lshl_or_b32 v149, v6, 4, v7
	v_or_b32_e32 v6, 2, v2
	v_bfe_u32 v8, v143, 1, 3
	v_bitop3_b32 v6, v4, v6, 7 bitop3:0x6c
	v_lshl_or_b32 v150, v6, 4, v5
	v_bitop3_b32 v6, v2, v8, 2 bitop3:0x36
	v_lshl_or_b32 v151, v6, 4, v7
	v_or_b32_e32 v6, 4, v2
	v_bitop3_b32 v6, v4, v6, 7 bitop3:0x6c
	v_lshl_or_b32 v152, v6, 4, v5
	v_bitop3_b32 v6, v2, v8, 4 bitop3:0x36
	v_lshl_or_b32 v153, v6, 4, v7
	v_or_b32_e32 v6, 6, v2
	s_add_i32 s0, s8, 1
	v_bitop3_b32 v9, v4, v2, 7 bitop3:0x6c
	v_bitop3_b32 v4, v4, v6, 7 bitop3:0x6c
	v_cvt_f32_i32_e32 v6, s0
	v_bitop3_b32 v2, v2, v8, 6 bitop3:0x36
	v_lshl_or_b32 v155, v2, 4, v7
	v_mul_f32_e32 v162, 0x3fb8aa3b, v3
	v_mul_f32_e32 v2, -0.5, v6
	v_cmp_gt_f32_e32 vcc, s4, v2
	s_and_b64 s[0:1], vcc, exec
	s_cselect_b32 s0, 0xffffffc0, 0
	v_cndmask_b32_e32 v2, 0, v140, vcc
	v_fmac_f32_e32 v2, -0.5, v6
	v_exp_f32_e32 v2, v2
	v_mov_b32_e32 v3, v1
	v_lshl_or_b32 v148, v9, 4, v5
	v_lshl_or_b32 v154, v4, 4, v5
	v_ldexp_f32 v2, v2, s0
	v_mul_f32_e32 v156, 0x3fb8aa3b, v2
	v_mov_b32_e32 v2, s16
	s_and_b32 s0, s16, 31
	v_and_b32_e32 v2, 31, v2
	s_lshl_b32 s8, s0, 6
	v_cmp_lt_u64_e32 vcc, 2, v[2:3]
	s_or_b32 s7, s8, s7
	s_addk_i32 s7, 0x80
	v_cndmask_b32_e32 v2, 2, v2, vcc
	v_lshlrev_b32_e32 v2, 13, v2
	s_max_u32 s0, s0, 2
	v_lshl_add_u64 v[4:5], s[10:11], 0, v[0:1]
	v_lshl_add_u64 v[6:7], s[78:79], 0, v[0:1]
	v_add_u32_e32 v0, s7, v144
	s_lshl_b32 s9, s0, 6
	s_and_b32 s0, s19, 0xffffff80
	v_lshl_add_u64 v[130:131], v[6:7], 0, v[2:3]
	v_lshl_add_u64 v[132:133], v[4:5], 0, v[2:3]
	v_sub_u32_e32 v0, v0, v146
	v_mov_b32_e32 v2, v1
	v_mov_b32_e32 v4, v1
	v_mov_b32_e32 v5, v1
	v_mov_b32_e32 v6, v1
	v_mov_b32_e32 v7, v1
	v_mov_b32_e32 v8, v1
	v_mov_b32_e32 v9, v1
	v_mov_b32_e32 v10, v1
	v_mov_b32_e32 v11, v1
	v_mov_b32_e32 v12, v1
	v_mov_b32_e32 v13, v1
	v_mov_b32_e32 v14, v1
	v_mov_b32_e32 v15, v1
	v_mov_b32_e32 v16, v1
	v_mov_b32_e32 v17, v1
	v_mov_b32_e32 v18, v1
	v_mov_b32_e32 v19, v1
	v_mov_b32_e32 v20, v1
	v_mov_b32_e32 v21, v1
	v_mov_b32_e32 v22, v1
	v_mov_b32_e32 v23, v1
	v_mov_b32_e32 v24, v1
	v_mov_b32_e32 v25, v1
	v_mov_b32_e32 v26, v1
	v_mov_b32_e32 v27, v1
	v_mov_b32_e32 v28, v1
	v_mov_b32_e32 v29, v1
	v_mov_b32_e32 v30, v1
	v_mov_b32_e32 v31, v1
	s_add_i32 s48, s0, 0
	v_readfirstlane_b32 s78, v156
	v_subrev_u32_e32 v159, s9, v0
	v_mov_b32_e32 v0, v1
	v_mov_b64_e32 v[32:33], v[30:31]
	s_mov_b32 s6, 0
	s_add_i32 s29, s29, -2
	s_add_i32 s30, s9, 0xffffff80
	s_add_i32 s31, s25, 0xffffff80
	s_add_i32 s33, s25, 0x9f
	s_or_b32 s40, s25, 31
	s_add_i32 s41, s25, 0xffffff9e
	s_add_i32 s48, s48, 0x20200
	v_mul_f32_e32 v157, 0x42000000, v156
	s_add_i32 s49, s25, 0x41
	v_or_b32_e32 v158, s25, v144
	s_mov_b32 s79, s78
	s_mov_b32 s50, s78
	s_mov_b32 s51, s78
	s_mov_b32 s72, s78
	s_mov_b32 s73, s78
	s_mov_b32 s94, s78
	s_mov_b32 s95, s78
	s_mov_b32 s96, s78
	s_mov_b32 s97, s78
	s_mov_b32 s2, s78
	s_mov_b32 s3, s78
	s_mov_b32 s13, s78
	s_mov_b32 s0, s78
	s_mov_b32 s1, s78
	s_mov_b32 s34, s78
	s_mov_b64 s[80:81], 0
	v_mov_b64_e32 v[30:31], v[28:29]
	v_mov_b64_e32 v[28:29], v[26:27]
	v_mov_b64_e32 v[26:27], v[24:25]
	v_mov_b64_e32 v[24:25], v[22:23]
	v_mov_b64_e32 v[22:23], v[20:21]
	v_mov_b64_e32 v[20:21], v[18:19]
	v_mov_b64_e32 v[18:19], v[16:17]
	v_mov_b64_e32 v[16:17], v[14:15]
	v_mov_b64_e32 v[14:15], v[12:13]
	v_mov_b64_e32 v[12:13], v[10:11]
	v_mov_b64_e32 v[10:11], v[8:9]
	v_mov_b64_e32 v[8:9], v[6:7]
	v_mov_b64_e32 v[6:7], v[4:5]
	v_mov_b64_e32 v[4:5], v[2:3]
	v_mov_b64_e32 v[2:3], v[0:1]
